# attention tail loop: same next-STEP G-table prefetch as the steady loop (Q regs free there too), on top of v11
# baseline (speedup 1.0000x reference)
.LBB0_1365:
	s_add_i32 s4, s10, s9
	s_lshl_b32 s5, s4, 6
	s_sub_i32 s28, s5, s30
	s_lshl_b32 s5, s10, 1
	s_lshl_b32 s3, s3, 3
	s_sub_i32 s3, s5, s3
	s_lshl_b32 s5, s9, 8
	s_add_i32 s11, s11, s5
	s_add_i32 s5, s11, 0
	s_sub_i32 s30, s10, s1
	s_add_i32 s5, s5, 0x14800
	s_sub_i32 s1, s4, s1
	s_add_i32 s27, s19, -2
	v_cmp_gt_u32_e64 s[40:41], 32, v204
	s_lshl_b32 s29, s9, 1
	s_add_i32 s10, s9, 2
	v_add_u32_e32 v1, s5, v209
	s_lshl_b32 s1, s1, 6
	ds_read_b128 v[188:191], v1
	ds_read_b128 v[192:195], v1 offset:32
	ds_read_b128 v[196:199], v1 offset:64
	ds_read_b128 v[220:223], v1 offset:96
	ds_read_b128 v[224:227], v1 offset:128
	ds_read_b128 v[228:231], v1 offset:160
	ds_read_b128 v[232:235], v1 offset:192
	ds_read_b128 v[236:239], v1 offset:224
.LBB0_1366:
	v_sub_f32_e32 v2, v214, v217
	s_waitcnt lgkmcnt(4)
	v_sub_f32_e32 v111, v2, v223
	v_sub_f32_e32 v110, v2, v222
	v_sub_f32_e32 v109, v2, v221
	v_sub_f32_e32 v108, v2, v220
	v_sub_f32_e32 v107, v2, v199
	v_sub_f32_e32 v106, v2, v198
	v_sub_f32_e32 v105, v2, v197
	v_sub_f32_e32 v104, v2, v196
	v_sub_f32_e32 v103, v2, v195
	v_sub_f32_e32 v102, v2, v194
	v_sub_f32_e32 v101, v2, v193
	v_sub_f32_e32 v100, v2, v192
	v_sub_f32_e32 v99, v2, v191
	v_sub_f32_e32 v98, v2, v190
	v_sub_f32_e32 v97, v2, v189
	v_sub_f32_e32 v96, v2, v188
	s_waitcnt lgkmcnt(0)
	v_sub_f32_e32 v95, v2, v239
	v_sub_f32_e32 v94, v2, v238
	v_sub_f32_e32 v93, v2, v237
	v_sub_f32_e32 v92, v2, v236
	v_sub_f32_e32 v91, v2, v235
	v_sub_f32_e32 v90, v2, v234
	v_sub_f32_e32 v89, v2, v233
	v_sub_f32_e32 v88, v2, v232
	v_sub_f32_e32 v87, v2, v231
	v_sub_f32_e32 v86, v2, v230
	v_sub_f32_e32 v85, v2, v229
	v_sub_f32_e32 v84, v2, v228
	v_sub_f32_e32 v83, v2, v227
	v_sub_f32_e32 v82, v2, v226
	v_sub_f32_e32 v81, v2, v225
	v_sub_f32_e32 v80, v2, v224
	ds_read_b128 v[188:191], v1 offset:256
	ds_read_b128 v[192:195], v1 offset:288
	ds_read_b128 v[196:199], v1 offset:320
	ds_read_b128 v[220:223], v1 offset:352
	ds_read_b128 v[224:227], v1 offset:384
	ds_read_b128 v[228:231], v1 offset:416
	ds_read_b128 v[232:235], v1 offset:448
	ds_read_b128 v[236:239], v1 offset:480
	v_add_u32_e32 v2, s14, v216
	ds_read_b64_tr_b16 v[4:5], v2 offset:24576
	ds_read_b64_tr_b16 v[6:7], v2 offset:25088
	v_mfma_f32_32x32x16_bf16 v[96:111], v[172:175], v[124:127], v[96:111]
	v_add_f32_e32 v8, v64, v65
	v_add_f32_e32 v8, v66, v8
	v_add_f32_e32 v8, v67, v8
	v_add_f32_e32 v8, v68, v8
	v_add_f32_e32 v12, v69, v8
	v_cvt_pk_bf16_f32 v140, v64, v65
	v_cvt_pk_bf16_f32 v141, v66, v67
	ds_read_b64_tr_b16 v[8:9], v2 offset:28672
	ds_read_b64_tr_b16 v[10:11], v2 offset:29184
	v_mfma_f32_32x32x16_bf16 v[80:95], v[168:171], v[124:127], v[80:95]
	v_add_f32_e32 v12, v70, v12
	v_add_f32_e32 v12, v71, v12
	v_add_f32_e32 v12, v72, v12
	v_add_f32_e32 v64, v73, v12
	v_cvt_pk_bf16_f32 v142, v68, v69
	v_cvt_pk_bf16_f32 v143, v70, v71
	ds_read_b64_tr_b16 v[12:13], v2 offset:25600
	ds_read_b64_tr_b16 v[14:15], v2 offset:26112
	v_mfma_f32_32x32x16_bf16 v[96:111], v[164:167], v[120:123], v[96:111]
	v_add_f32_e32 v64, v74, v64
	v_add_f32_e32 v64, v75, v64
	v_add_f32_e32 v64, v76, v64
	v_add_f32_e32 v68, v77, v64
	v_cvt_pk_bf16_f32 v136, v72, v73
	v_cvt_pk_bf16_f32 v137, v74, v75
	ds_read_b64_tr_b16 v[64:65], v2 offset:29696
	ds_read_b64_tr_b16 v[66:67], v2 offset:30208
	v_mfma_f32_32x32x16_bf16 v[80:95], v[160:163], v[120:123], v[80:95]
	v_add_f32_e32 v68, v78, v68
	v_add_f32_e32 v68, v79, v68
	v_add_f32_e32 v68, v48, v68
	v_add_f32_e32 v72, v49, v68
	v_cvt_pk_bf16_f32 v138, v76, v77
	v_cvt_pk_bf16_f32 v139, v78, v79
	ds_read_b64_tr_b16 v[68:69], v2 offset:26624
	ds_read_b64_tr_b16 v[70:71], v2 offset:27136
	v_mfma_f32_32x32x16_bf16 v[96:111], v[156:159], v[116:119], v[96:111]
	v_add_f32_e32 v72, v50, v72
	v_add_f32_e32 v72, v51, v72
	v_add_f32_e32 v72, v52, v72
	v_add_f32_e32 v72, v53, v72
	v_cvt_pk_bf16_f32 v132, v48, v49
	v_cvt_pk_bf16_f32 v133, v50, v51
	ds_read_b64_tr_b16 v[48:49], v2 offset:30720
	ds_read_b64_tr_b16 v[50:51], v2 offset:31232
	v_mfma_f32_32x32x16_bf16 v[80:95], v[152:155], v[116:119], v[80:95]
	v_add_f32_e32 v72, v54, v72
	v_add_f32_e32 v72, v55, v72
	v_add_f32_e32 v72, v56, v72
	v_add_f32_e32 v72, v57, v72
	v_cvt_pk_bf16_f32 v134, v52, v53
	v_cvt_pk_bf16_f32 v135, v54, v55
	ds_read_b64_tr_b16 v[52:53], v2 offset:27648
	ds_read_b64_tr_b16 v[54:55], v2 offset:28160
	v_mfma_f32_32x32x16_bf16 v[96:111], v[148:151], v[112:115], v[96:111]
	v_add_f32_e32 v72, v58, v72
	v_add_f32_e32 v72, v59, v72
	v_add_f32_e32 v72, v60, v72
	v_add_f32_e32 v72, v61, v72
	v_cvt_pk_bf16_f32 v128, v56, v57
	v_cvt_pk_bf16_f32 v129, v58, v59
	ds_read_b64_tr_b16 v[56:57], v2 offset:31744
	ds_read_b64_tr_b16 v[58:59], v2 offset:32256
	v_mfma_f32_32x32x16_bf16 v[80:95], v[144:147], v[112:115], v[80:95]
	v_add_f32_e32 v2, v62, v72
	v_add_f32_e32 v2, v63, v2
	v_add_f32_e32 v2, 0, v2
	v_cvt_pk_bf16_f32 v130, v60, v61
	v_cvt_pk_bf16_f32 v131, v62, v63
	s_add_i32 s64, s10, 1
	s_cmp_ge_i32 s64, s24
	s_cselect_b64 s[8:9], -1, 0
	s_and_b64 vcc, exec, s[8:9]
	s_cbranch_vccnz .LBB0_1368
	s_lshl_b64 s[4:5], s[64:65], 17
	v_lshl_add_u64 v[60:61], v[200:201], 0, s[4:5]
	s_add_i32 s4, s25, s21
	s_mov_b32 s5, m0
	s_mov_b32 m0, s4
	s_nop 0
	global_load_lds_dwordx4 v[60:61], off
	s_mov_b32 m0, s5

.LBB0_1375:
	v_sub_f32_e32 v128, v214, v217
	s_waitcnt lgkmcnt(4)
	v_sub_f32_e32 v79, v128, v223
	v_sub_f32_e32 v78, v128, v222
	v_sub_f32_e32 v77, v128, v221
	v_sub_f32_e32 v76, v128, v220
	v_sub_f32_e32 v75, v128, v199
	v_sub_f32_e32 v74, v128, v198
	v_sub_f32_e32 v73, v128, v197
	v_sub_f32_e32 v72, v128, v196
	v_sub_f32_e32 v71, v128, v195
	v_sub_f32_e32 v70, v128, v194
	v_sub_f32_e32 v69, v128, v193
	v_sub_f32_e32 v68, v128, v192
	v_sub_f32_e32 v67, v128, v191
	v_sub_f32_e32 v66, v128, v190
	v_sub_f32_e32 v65, v128, v189
	v_sub_f32_e32 v64, v128, v188
	s_waitcnt lgkmcnt(0)
	v_sub_f32_e32 v63, v128, v239
	v_sub_f32_e32 v62, v128, v238
	v_sub_f32_e32 v61, v128, v237
	v_sub_f32_e32 v60, v128, v236
	v_sub_f32_e32 v59, v128, v235
	v_sub_f32_e32 v58, v128, v234
	v_sub_f32_e32 v57, v128, v233
	v_sub_f32_e32 v56, v128, v232
	v_sub_f32_e32 v55, v128, v231
	v_sub_f32_e32 v54, v128, v230
	v_sub_f32_e32 v53, v128, v229
	v_sub_f32_e32 v52, v128, v228
	v_sub_f32_e32 v51, v128, v227
	v_sub_f32_e32 v50, v128, v226
	v_sub_f32_e32 v49, v128, v225
	v_sub_f32_e32 v48, v128, v224
	ds_read_b128 v[188:191], v1 offset:512
	ds_read_b128 v[192:195], v1 offset:544
	ds_read_b128 v[196:199], v1 offset:576
	ds_read_b128 v[220:223], v1 offset:608
	ds_read_b128 v[224:227], v1 offset:640
	ds_read_b128 v[228:231], v1 offset:672
	ds_read_b128 v[232:235], v1 offset:704
	ds_read_b128 v[236:239], v1 offset:736
	v_add_u32_e32 v6, s25, v216
	ds_read_b64_tr_b16 v[184:185], v6 offset:24576
	ds_read_b64_tr_b16 v[186:187], v6 offset:25088
	v_mfma_f32_32x32x16_bf16 v[64:79], v[172:175], v[124:127], v[64:79]
	v_add_f32_e32 v4, v96, v97
	v_add_f32_e32 v4, v98, v4
	v_add_f32_e32 v4, v99, v4
	v_add_f32_e32 v4, v100, v4
	v_add_f32_e32 v4, v101, v4
	v_cvt_pk_bf16_f32 v140, v96, v97
	v_cvt_pk_bf16_f32 v141, v98, v99
	ds_read_b64_tr_b16 v[180:181], v6 offset:28672
	ds_read_b64_tr_b16 v[182:183], v6 offset:29184
	v_mfma_f32_32x32x16_bf16 v[48:63], v[168:171], v[124:127], v[48:63]
	v_add_f32_e32 v4, v102, v4
	v_add_f32_e32 v4, v103, v4
	v_add_f32_e32 v4, v104, v4
	v_add_f32_e32 v4, v105, v4
	v_cvt_pk_bf16_f32 v142, v100, v101
	v_cvt_pk_bf16_f32 v143, v102, v103
	ds_read_b64_tr_b16 v[176:177], v6 offset:25600
	ds_read_b64_tr_b16 v[178:179], v6 offset:26112
	v_mfma_f32_32x32x16_bf16 v[64:79], v[164:167], v[120:123], v[64:79]
	v_add_f32_e32 v4, v106, v4
	v_add_f32_e32 v4, v107, v4
	v_add_f32_e32 v4, v108, v4
	v_add_f32_e32 v4, v109, v4
	v_cvt_pk_bf16_f32 v136, v104, v105
	v_cvt_pk_bf16_f32 v137, v106, v107
	ds_read_b64_tr_b16 v[100:101], v6 offset:29696
	ds_read_b64_tr_b16 v[102:103], v6 offset:30208
	v_mfma_f32_32x32x16_bf16 v[48:63], v[160:163], v[120:123], v[48:63]
	v_add_f32_e32 v4, v110, v4
	v_add_f32_e32 v4, v111, v4
	v_add_f32_e32 v4, v80, v4
	v_add_f32_e32 v4, v81, v4
	v_cvt_pk_bf16_f32 v138, v108, v109
	v_cvt_pk_bf16_f32 v139, v110, v111
	ds_read_b64_tr_b16 v[96:97], v6 offset:26624
	ds_read_b64_tr_b16 v[98:99], v6 offset:27136
	v_mfma_f32_32x32x16_bf16 v[64:79], v[156:159], v[116:119], v[64:79]
	v_add_f32_e32 v4, v82, v4
	v_add_f32_e32 v4, v83, v4
	v_add_f32_e32 v4, v84, v4
	v_add_f32_e32 v4, v85, v4
	v_cvt_pk_bf16_f32 v132, v80, v81
	v_cvt_pk_bf16_f32 v133, v82, v83
	ds_read_b64_tr_b16 v[12:13], v6 offset:30720
	ds_read_b64_tr_b16 v[14:15], v6 offset:31232
	v_mfma_f32_32x32x16_bf16 v[48:63], v[152:155], v[116:119], v[48:63]
	v_add_f32_e32 v4, v86, v4
	v_add_f32_e32 v4, v87, v4
	v_add_f32_e32 v4, v88, v4
	v_add_f32_e32 v4, v89, v4
	v_cvt_pk_bf16_f32 v134, v84, v85
	v_cvt_pk_bf16_f32 v135, v86, v87
	ds_read_b64_tr_b16 v[8:9], v6 offset:27648
	ds_read_b64_tr_b16 v[10:11], v6 offset:28160
	v_mfma_f32_32x32x16_bf16 v[64:79], v[148:151], v[112:115], v[64:79]
	v_add_f32_e32 v4, v90, v4
	v_add_f32_e32 v4, v91, v4
	v_add_f32_e32 v4, v92, v4
	v_add_f32_e32 v80, v93, v4
	v_cvt_pk_bf16_f32 v128, v88, v89
	v_cvt_pk_bf16_f32 v129, v90, v91
	ds_read_b64_tr_b16 v[4:5], v6 offset:31744
	ds_read_b64_tr_b16 v[6:7], v6 offset:32256
	v_mfma_f32_32x32x16_bf16 v[48:63], v[144:147], v[112:115], v[48:63]
	v_add_f32_e32 v80, v94, v80
	v_add_f32_e32 v80, v95, v80
	v_add_f32_e32 v80, 0, v80
	v_cvt_pk_bf16_f32 v130, v92, v93
	v_cvt_pk_bf16_f32 v131, v94, v95
	s_add_i32 s64, s10, 2
	s_cmp_ge_i32 s64, s24
	s_cselect_b64 s[12:13], -1, 0
	s_and_b64 vcc, exec, s[12:13]
	s_cbranch_vccnz .LBB0_1377
	s_lshl_b64 s[4:5], s[64:65], 17
	v_lshl_add_u64 v[82:83], v[200:201], 0, s[4:5]
	s_add_i32 s4, s0, s21
	s_mov_b32 s5, m0
	s_mov_b32 m0, s4
	s_nop 0
	global_load_lds_dwordx4 v[82:83], off
	s_mov_b32 m0, s5
